# all w_ff2 conversion items moved into the FFN-up GEMM idle tail (phase C keeps none after layer 0), tail conversion loops un-serialized
# speedup vs baseline: 1.0043x; 1.0043x over previous
; __device__ __forceinline__ void transpose_item(const float* W, int K, int N, int NP, bf16* WT, LAS float* scr, int item, int lane, const LAS float* tab, long long* bias, int ldb, const float* kscale = nullptr) {
;     const int nblk = NP / 32, kb = item / nblk, nb = item - kb * nblk, k0 = 64 * kb, n0 = 32 * nb;
;     const int n = n0 + (lane & 31); const bool okn = n < N;
;     float wv_[32];
;     const float* wp = W + (size_t)(k0 + (lane >> 5)) * N + (okn ? n : 0);
; #pragma unroll
;     for (int i = 0; i < 32; ++i) wv_[i] = wp[(size_t)(2 * i) * N];
; __global__ void __launch_bounds__(NTHR, 2) fwd_kernel(Args a) {
;     ...
;           const bool needA0 = l == 0 || !g1tail, needA1 = l == 0 || !g4tail;
;           if (needA0 || needA1) { conv_load_tab(tab, modl, 3, tid);
;               if (needA0) conv_A(csrc, cdst, l, 0, CV_A_SPLIT, gw, NGW, scr, tab, biasl, lane);
;               if (needA1) { conv_A(csrc, cdst, l, CV_A_SPLIT, CV_I1, gw, NGW, scr, tab, biasl, lane); conv_B(csrc, cdst, l, 0, CV_B_SPLIT, gw, NGW, scr, lane); } }
;           conv_B(csrc, cdst, l, CV_B_SPLIT, CV_I2, gw, NGW, scr, lane);
.LBB0_127:
	s_cmpk_gt_i32 s24, 0x1fff
	s_mov_b32 s18, 0xc000
	s_cbranch_scc1 .LBB0_130
	v_readlane_b32 s2, v254, 63
	v_readlane_b32 s4, v252, 16
	v_readlane_b32 s3, v255, 0
	s_lshl_b32 s2, s2, 26
	v_readlane_b32 s8, v252, 20
	v_lshlrev_b32_e32 v4, 3, v1
	s_add_u32 s4, s8, s2
	v_and_b32_e32 v4, 56, v4
	v_readlane_b32 s2, v254, 57
	v_readlane_b32 s5, v252, 17
	v_readlane_b32 s9, v252, 21
	v_and_b32_e32 v8, 31, v2
	v_lshrrev_b32_e32 v3, 5, v1
	v_lshrrev_b32_e32 v7, 3, v1
	v_lshlrev_b32_e32 v32, 1, v4
	v_readlane_b32 s3, v254, 58
	v_readlane_b32 s6, v252, 18
	v_readlane_b32 s7, v252, 19
	v_readlane_b32 s10, v252, 22
	v_readlane_b32 s11, v252, 23
	s_addc_u32 s5, s9, 0
	v_lshl_add_u32 v9, v8, 2, s28
	v_mul_u32_u24_e32 v10, 0x84, v3
	v_mul_u32_u24_e32 v6, 0x84, v4
	v_lshl_add_u64 v[4:5], s[2:3], 0, v[32:33]
	v_lshlrev_b32_e32 v11, 2, v7
	s_lshl_b32 s2, s26, 8
	v_add3_u32 v6, s28, v6, v11
	s_lshl_b32 s6, s27, 5
	v_or_b32_e32 v7, s2, v7
	v_or_b32_e32 v8, s2, v8
	v_add_u32_e32 v9, v9, v10
	s_mov_b32 s7, s24
	s_mov_b32 s8, 0x1c000
	s_mov_b32 s9, 0x24000
	s_mov_b32 s10, 0x28000
	s_mov_b32 s11, 0x2c000
	s_mov_b32 s13, 0x34000
	s_mov_b32 s14, 0x38000
	s_mov_b32 s15, 0x44000
	s_mov_b32 s31, 0x6c000
	s_mov_b32 s25, 0x74000
	s_mov_b32 s16, 0x48000
	s_mov_b32 s17, 0x4c000
	s_mov_b32 s19, 0x54000
	s_mov_b32 s22, 0x58000
	s_mov_b32 s23, 0x5c000
	s_mov_b32 s72, 0x64000
	s_mov_b32 s73, 0x68000
	s_mov_b32 s82, 0x78000
	s_movk_i32 s46, 0x4000
.LBB0_129:
	s_ashr_i32 s2, s7, 31
	s_lshr_b32 s2, s2, 26
	s_add_i32 s3, s7, s2
	s_and_b32 s2, s3, 0xffffffc0
	s_lshl_b32 s3, s3, 5
	s_and_b32 s12, s3, 0xfffff800
	s_sub_i32 s12, s6, s12
	v_or_b32_e32 v10, s2, v3
	v_add_u32_e32 v15, s12, v8
	v_ashrrev_i32_e32 v11, 31, v10
	v_cmp_gt_i32_e32 vcc, s56, v15
	v_lshlrev_b64 v[10:11], 13, v[10:11]
	v_add_u32_e32 v14, s12, v7
	v_cndmask_b32_e32 v16, 0, v15, vcc
	s_ashr_i32 s3, s2, 31
	v_lshl_add_u64 v[10:11], s[4:5], 0, v[10:11]
	v_ashrrev_i32_e32 v15, 31, v14
	v_add_u32_e32 v18, 8, v14
	v_ashrrev_i32_e32 v17, 31, v16
	v_lshl_add_u64 v[12:13], s[2:3], 1, v[4:5]
	v_add_u32_e32 v20, 16, v14
	v_add_u32_e32 v22, 24, v14
	v_lshlrev_b64 v[14:15], 14, v[14:15]
	v_ashrrev_i32_e32 v19, 31, v18
	v_lshl_add_u64 v[10:11], v[16:17], 2, v[10:11]
	v_lshl_add_u64 v[26:27], v[12:13], 0, v[14:15]
	v_lshlrev_b64 v[14:15], 14, v[18:19]
	v_add_co_u32_e64 v18, s[2:3], s46, v10
	v_ashrrev_i32_e32 v21, 31, v20
	s_nop 0
	v_addc_co_u32_e64 v19, s[2:3], 0, v11, s[2:3]
	v_lshlrev_b64 v[16:17], 14, v[20:21]
	v_add_co_u32_e64 v20, s[2:3], s41, v10
	v_ashrrev_i32_e32 v23, 31, v22
	s_nop 0
	v_addc_co_u32_e64 v21, s[2:3], 0, v11, s[2:3]
	v_add_co_u32_e64 v24, s[2:3], s18, v10
	v_add_u32_e32 v32, 0x400, v9
	s_nop 0
	v_addc_co_u32_e64 v25, s[2:3], 0, v11, s[2:3]
	v_add_co_u32_e64 v28, s[2:3], s92, v10
	v_add_u32_e32 v86, 0x800, v9
	s_nop 0
	v_addc_co_u32_e64 v29, s[2:3], 0, v11, s[2:3]
	v_add_co_u32_e64 v30, s[2:3], s60, v10
	v_add_u32_e32 v87, 0xc00, v9
	s_nop 0
	v_addc_co_u32_e64 v31, s[2:3], 0, v11, s[2:3]
	v_add_co_u32_e64 v34, s[2:3], s61, v10
	v_add_u32_e32 v88, 0x1000, v9
	s_nop 0
	v_addc_co_u32_e64 v35, s[2:3], 0, v11, s[2:3]
	v_add_co_u32_e64 v36, s[2:3], s8, v10
	v_add_u32_e32 v89, 0x1400, v9
	s_nop 0
	v_addc_co_u32_e64 v37, s[2:3], 0, v11, s[2:3]
	v_add_co_u32_e64 v38, s[2:3], s78, v10
	v_add_u32_e32 v90, 0x1800, v9
	s_nop 0
	v_addc_co_u32_e64 v39, s[2:3], 0, v11, s[2:3]
	v_add_co_u32_e64 v40, s[2:3], s9, v10
	v_add_u32_e32 v91, 0x1c00, v9
	s_nop 0
	v_addc_co_u32_e64 v41, s[2:3], 0, v11, s[2:3]
	v_add_co_u32_e64 v42, s[2:3], s10, v10
	s_add_i32 s7, s7, s76
	s_nop 0
	v_addc_co_u32_e64 v43, s[2:3], 0, v11, s[2:3]
	v_add_co_u32_e64 v44, s[2:3], s11, v10
	v_add_u32_e32 v7, s53, v7
	s_nop 0
	v_addc_co_u32_e64 v45, s[2:3], 0, v11, s[2:3]
	v_add_co_u32_e64 v46, s[2:3], s49, v10
	s_cmpk_lt_i32 s7, 0x2000
	s_nop 0
	v_addc_co_u32_e64 v47, s[2:3], 0, v11, s[2:3]
	v_add_co_u32_e64 v48, s[2:3], s13, v10
	v_add_u32_e32 v8, s53, v8
	s_nop 0
	v_addc_co_u32_e64 v49, s[2:3], 0, v11, s[2:3]
	v_add_co_u32_e64 v50, s[2:3], s14, v10
	s_nop 1
	v_addc_co_u32_e64 v51, s[2:3], 0, v11, s[2:3]
	v_add_co_u32_e64 v52, s[2:3], s39, v10
	s_nop 1
	v_addc_co_u32_e64 v53, s[2:3], 0, v11, s[2:3]
	v_add_co_u32_e64 v54, s[2:3], s79, v10
	s_nop 1
	v_addc_co_u32_e64 v55, s[2:3], 0, v11, s[2:3]
	v_add_co_u32_e64 v56, s[2:3], s15, v10
	s_nop 1
	v_addc_co_u32_e64 v57, s[2:3], 0, v11, s[2:3]
	v_add_co_u32_e64 v58, s[2:3], s16, v10
	s_nop 1
	v_addc_co_u32_e64 v59, s[2:3], 0, v11, s[2:3]
	v_add_co_u32_e64 v60, s[2:3], s17, v10
	s_nop 1
	v_addc_co_u32_e64 v61, s[2:3], 0, v11, s[2:3]
	v_add_co_u32_e64 v62, s[2:3], s0, v10
	s_nop 1
	v_addc_co_u32_e64 v63, s[2:3], 0, v11, s[2:3]
	v_add_co_u32_e64 v64, s[2:3], s19, v10
	s_nop 1
	v_addc_co_u32_e64 v65, s[2:3], 0, v11, s[2:3]
	v_add_co_u32_e64 v66, s[2:3], s22, v10
	s_nop 1
	v_addc_co_u32_e64 v67, s[2:3], 0, v11, s[2:3]
	v_add_co_u32_e64 v68, s[2:3], s23, v10
	s_nop 1
	v_addc_co_u32_e64 v69, s[2:3], 0, v11, s[2:3]
	v_add_co_u32_e64 v70, s[2:3], s40, v10
	s_nop 1
	v_addc_co_u32_e64 v71, s[2:3], 0, v11, s[2:3]
	v_add_co_u32_e64 v72, s[2:3], s72, v10
	s_nop 1
	v_addc_co_u32_e64 v73, s[2:3], 0, v11, s[2:3]
	v_add_co_u32_e64 v74, s[2:3], s73, v10
	s_nop 1
	v_addc_co_u32_e64 v75, s[2:3], 0, v11, s[2:3]
	v_add_co_u32_e64 v76, s[2:3], s31, v10
	s_nop 1
	v_addc_co_u32_e64 v77, s[2:3], 0, v11, s[2:3]
	v_add_co_u32_e64 v78, s[2:3], s96, v10
	s_nop 1
	v_addc_co_u32_e64 v79, s[2:3], 0, v11, s[2:3]
	v_add_co_u32_e64 v80, s[2:3], s25, v10
	s_nop 1
	v_addc_co_u32_e64 v81, s[2:3], 0, v11, s[2:3]
	v_add_co_u32_e64 v82, s[2:3], s82, v10
	s_nop 1
	v_addc_co_u32_e64 v83, s[2:3], 0, v11, s[2:3]
	v_add_co_u32_e64 v84, s[2:3], s83, v10
; #define LAS __attribute__((address_space(3)))
; #define LDS_WAIT() asm volatile("s_waitcnt lgkmcnt(0)" ::: "memory")
; __device__ __forceinline__ unsigned pk2(float lo, float hi) { return pg8::pkbf(lo, hi); }
; __device__ __forceinline__ void transpose_item(const float* W, int K, int N, int NP, bf16* WT, LAS float* scr, int item, int lane, const LAS float* tab, long long* bias, int ldb, const float* kscale = nullptr) {
;     ...
;     for (int i = 0; i < 32; ++i) wv_[i] = wp[(size_t)(2 * i) * N];
; #pragma unroll
;     for (int i = 0; i < 32; ++i) { if (!okn) wv_[i] = 0.f; if (kscale != nullptr) wv_[i] *= kscale[k0 + 2 * i + (lane >> 5)]; scr[(2 * i + (lane >> 5)) * 33 + (lane & 31)] = wv_[i]; }
;     if (tab != nullptr) {
;         const LAS float* tp = tab + k0 + (lane >> 5);
; #pragma unroll
;         for (int bp = 0; bp < 5; ++bp) { float s = 0.f;
; #pragma unroll
;             for (int i = 0; i < 32; ++i) s += tp[bp * 2048 + 2 * i] * wv_[i];
;             s += __shfl_xor(s, 32);
;             if (lane < 32) atomicAdd((unsigned long long*)(bias + (size_t)bp * ldb + n), (unsigned long long)(long long)(s * 4294967296.f)); }
;     }
;     LDS_WAIT(); asm volatile("" ::: "memory");
;     const int c = lane & 7;
; #pragma unroll
;     for (int j = 0; j < 4; ++j) { const int nn = (lane >> 3) + 8 * j; const LAS float* s = scr + (8 * c) * 33 + nn;
;         v4u o; o.x = pk2(s[0 * 33], s[1 * 33]); o.y = pk2(s[2 * 33], s[3 * 33]); o.z = pk2(s[4 * 33], s[5 * 33]); o.w = pk2(s[6 * 33], s[7 * 33]);
;         *(v4u*)(WT + (size_t)(n0 + nn) * K + k0 + 8 * c) = o; }
;     LDS_WAIT(); asm volatile("" ::: "memory");
	s_nop 1
	v_addc_co_u32_e64 v85, s[2:3], 0, v11, s[2:3]
	global_load_dword v92, v[10:11], off
	s_nop 0
	global_load_dword v18, v[18:19], off
	s_nop 0
	global_load_dword v19, v[20:21], off
	s_nop 0
	global_load_dword v20, v[24:25], off
	global_load_dword v21, v[28:29], off
	s_nop 0
	global_load_dword v24, v[30:31], off
	global_load_dword v25, v[34:35], off
	s_nop 0
	global_load_dword v36, v[36:37], off
	s_nop 0
	global_load_dword v37, v[38:39], off
	s_nop 0
	global_load_dword v38, v[40:41], off
	global_load_dword v39, v[42:43], off
	s_nop 0
	global_load_dword v40, v[44:45], off
	global_load_dword v41, v[46:47], off
	global_load_dword v42, v[48:49], off
	global_load_dword v43, v[50:51], off
	s_nop 0
	global_load_dword v44, v[52:53], off
	global_load_dword v45, v[54:55], off
	global_load_dword v46, v[56:57], off
	global_load_dword v47, v[58:59], off
	global_load_dword v48, v[60:61], off
	global_load_dword v49, v[62:63], off
	global_load_dword v50, v[64:65], off
	global_load_dword v51, v[66:67], off
	global_load_dword v52, v[68:69], off
	global_load_dword v53, v[70:71], off
	global_load_dword v54, v[72:73], off
	global_load_dword v55, v[74:75], off
	global_load_dword v56, v[76:77], off
	global_load_dword v57, v[78:79], off
	global_load_dword v58, v[80:81], off
	global_load_dword v59, v[82:83], off
	global_load_dword v60, v[84:85], off
	v_lshlrev_b64 v[10:11], 14, v[22:23]
	v_lshl_add_u64 v[34:35], v[12:13], 0, v[10:11]
	v_lshl_add_u64 v[28:29], v[12:13], 0, v[14:15]
	v_lshl_add_u64 v[30:31], v[12:13], 0, v[16:17]
	s_waitcnt vmcnt(31)
	v_cndmask_b32_e32 v10, 0, v92, vcc
	s_waitcnt vmcnt(30)
	v_cndmask_b32_e32 v11, 0, v18, vcc
	s_waitcnt vmcnt(29)
	v_cndmask_b32_e32 v12, 0, v19, vcc
	s_waitcnt vmcnt(28)
	v_cndmask_b32_e32 v13, 0, v20, vcc
	s_waitcnt vmcnt(27)
	v_cndmask_b32_e32 v14, 0, v21, vcc
	s_waitcnt vmcnt(26)
	v_cndmask_b32_e32 v15, 0, v24, vcc
	s_waitcnt vmcnt(25)
	v_cndmask_b32_e32 v16, 0, v25, vcc
	s_waitcnt vmcnt(24)
	v_cndmask_b32_e32 v17, 0, v36, vcc
	s_waitcnt vmcnt(23)
	v_cndmask_b32_e32 v18, 0, v37, vcc
	s_waitcnt vmcnt(22)
	v_cndmask_b32_e32 v19, 0, v38, vcc
	s_waitcnt vmcnt(21)
	v_cndmask_b32_e32 v20, 0, v39, vcc
	s_waitcnt vmcnt(20)
	v_cndmask_b32_e32 v21, 0, v40, vcc
	s_waitcnt vmcnt(19)
	v_cndmask_b32_e32 v22, 0, v41, vcc
	s_waitcnt vmcnt(18)
	v_cndmask_b32_e32 v23, 0, v42, vcc
	s_waitcnt vmcnt(17)
	v_cndmask_b32_e32 v24, 0, v43, vcc
	s_waitcnt vmcnt(16)
	v_cndmask_b32_e32 v25, 0, v44, vcc
	s_waitcnt vmcnt(15)
	v_cndmask_b32_e32 v36, 0, v45, vcc
	s_waitcnt vmcnt(14)
	v_cndmask_b32_e32 v37, 0, v46, vcc
	s_waitcnt vmcnt(13)
	v_cndmask_b32_e32 v38, 0, v47, vcc
	s_waitcnt vmcnt(12)
	v_cndmask_b32_e32 v39, 0, v48, vcc
	s_waitcnt vmcnt(11)
	v_cndmask_b32_e32 v40, 0, v49, vcc
	s_waitcnt vmcnt(10)
	v_cndmask_b32_e32 v41, 0, v50, vcc
	s_waitcnt vmcnt(9)
	v_cndmask_b32_e32 v42, 0, v51, vcc
	s_waitcnt vmcnt(8)
	v_cndmask_b32_e32 v43, 0, v52, vcc
	s_waitcnt vmcnt(7)
	v_cndmask_b32_e32 v44, 0, v53, vcc
	s_waitcnt vmcnt(6)
	v_cndmask_b32_e32 v45, 0, v54, vcc
	s_waitcnt vmcnt(5)
	v_cndmask_b32_e32 v46, 0, v55, vcc
	s_waitcnt vmcnt(4)
	v_cndmask_b32_e32 v47, 0, v56, vcc
	s_waitcnt vmcnt(3)
	v_cndmask_b32_e32 v48, 0, v57, vcc
	s_waitcnt vmcnt(2)
	v_cndmask_b32_e32 v49, 0, v58, vcc
	s_waitcnt vmcnt(1)
	v_cndmask_b32_e32 v50, 0, v59, vcc
	s_waitcnt vmcnt(0)
	v_cndmask_b32_e32 v51, 0, v60, vcc
	ds_write2_b32 v9, v10, v11 offset1:66
	ds_write2_b32 v9, v12, v13 offset0:132 offset1:198
	ds_write2_b32 v32, v14, v15 offset0:8 offset1:74
	ds_write2_b32 v32, v16, v17 offset0:140 offset1:206
	ds_write2_b32 v86, v18, v19 offset0:16 offset1:82
	ds_write2_b32 v86, v20, v21 offset0:148 offset1:214
	ds_write2_b32 v87, v22, v23 offset0:24 offset1:90
	ds_write2_b32 v87, v24, v25 offset0:156 offset1:222
	ds_write2_b32 v88, v36, v37 offset0:32 offset1:98
	ds_write2_b32 v88, v38, v39 offset0:164 offset1:230
	ds_write2_b32 v89, v40, v41 offset0:40 offset1:106
	ds_write2_b32 v89, v42, v43 offset0:172 offset1:238
	ds_write2_b32 v90, v44, v45 offset0:48 offset1:114
	ds_write2_b32 v90, v46, v47 offset0:180 offset1:246
	ds_write2_b32 v91, v48, v49 offset0:56 offset1:122
	ds_write2_b32 v91, v50, v51 offset0:188 offset1:254
	s_waitcnt lgkmcnt(0)
	ds_read2_b32 v[14:15], v6 offset0:33 offset1:41
	ds_read2_b32 v[16:17], v6 offset1:8
	ds_read2_b32 v[18:19], v6 offset0:66 offset1:74
	ds_read2_b32 v[20:21], v6 offset0:99 offset1:107
	ds_read2_b32 v[22:23], v6 offset0:132 offset1:140
	ds_read2_b32 v[24:25], v6 offset0:165 offset1:173
	ds_read2_b32 v[36:37], v6 offset0:198 offset1:206
	ds_read2_b32 v[38:39], v6 offset0:231 offset1:239
	ds_read2_b32 v[40:41], v6 offset0:49 offset1:57
	ds_read2_b32 v[42:43], v6 offset0:16 offset1:24
	ds_read2_b32 v[44:45], v6 offset0:82 offset1:90
	ds_read2_b32 v[46:47], v6 offset0:115 offset1:123
	ds_read2_b32 v[48:49], v6 offset0:148 offset1:156
	ds_read2_b32 v[50:51], v6 offset0:181 offset1:189
	ds_read2_b32 v[52:53], v6 offset0:214 offset1:222
	ds_read2_b32 v[54:55], v6 offset0:247 offset1:255
	s_waitcnt lgkmcnt(14)
	v_cvt_pk_bf16_f32 v10, v16, v14
	s_waitcnt lgkmcnt(12)
	v_cvt_pk_bf16_f32 v11, v18, v20
	s_waitcnt lgkmcnt(10)
	v_cvt_pk_bf16_f32 v12, v22, v24
	s_waitcnt lgkmcnt(8)
	v_cvt_pk_bf16_f32 v13, v36, v38
	v_cvt_pk_bf16_f32 v14, v17, v15
	v_cvt_pk_bf16_f32 v15, v19, v21
	v_cvt_pk_bf16_f32 v16, v23, v25
	v_cvt_pk_bf16_f32 v17, v37, v39
	s_waitcnt lgkmcnt(6)
	v_cvt_pk_bf16_f32 v18, v42, v40
	s_waitcnt lgkmcnt(4)
	v_cvt_pk_bf16_f32 v19, v44, v46
	s_waitcnt lgkmcnt(2)
	v_cvt_pk_bf16_f32 v20, v48, v50
	s_waitcnt lgkmcnt(0)
	v_cvt_pk_bf16_f32 v21, v52, v54
	v_cvt_pk_bf16_f32 v22, v43, v41
	v_cvt_pk_bf16_f32 v23, v45, v47
	v_cvt_pk_bf16_f32 v24, v49, v51
	v_cvt_pk_bf16_f32 v25, v53, v55
	global_store_dwordx4 v[26:27], v[10:13], off
	global_store_dwordx4 v[28:29], v[14:17], off
	global_store_dwordx4 v[30:31], v[18:21], off
	global_store_dwordx4 v[34:35], v[22:25], off
	s_waitcnt lgkmcnt(0)
	s_cbranch_scc1 .LBB0_129
; #define LAS __attribute__((address_space(3)))
; __device__ __forceinline__ void conv_B(const ConvSrc s, const ConvDst d, int l, int lo, int hi, int worker, int nworkers, LAS float* scr, int lane) {
;     for (int it = lo + worker; it < hi; it += nworkers) transpose_item(s.w2 + (size_t)l * DFF * DM, DFF, DM, DM, d.w2, scr, it, lane, nullptr, nullptr, 0);
; __global__ void __launch_bounds__(NTHR, 2) fwd_kernel(Args a) {
;     ...
;               if (needA1) { conv_A(csrc, cdst, l, CV_A_SPLIT, CV_I1, gw, NGW, scr, tab, biasl, lane); conv_B(csrc, cdst, l, 0, CV_B_SPLIT, gw, NGW, scr, lane); } }
;           conv_B(csrc, cdst, l, CV_B_SPLIT, CV_I2, gw, NGW, scr, lane);
.LBB0_130:
	s_add_i32 s12, s24, 0x2000
	v_lshrrev_b32_e32 v45, 5, v1
	v_lshrrev_b32_e32 v46, 3, v1
	v_lshlrev_b32_e32 v3, 3, v1
	s_cmpk_gt_i32 s12, 0x1fff
	v_and_b32_e32 v44, 31, v2
	v_mul_u32_u24_e32 v8, 0x84, v45
	v_and_b32_e32 v7, 56, v3
	v_lshlrev_b32_e32 v6, 2, v46
	s_mov_b32 s15, 0x1c000
	s_mov_b32 s16, 0x24000
	s_mov_b32 s17, 0x28000
	s_mov_b32 s19, 0x2c000
	s_mov_b32 s22, 0x34000
	s_mov_b32 s23, 0x38000
	s_mov_b32 s72, 0x44000
	s_mov_b32 s73, 0x4c000
	s_cbranch_scc1 .LBB0_133
	v_readlane_b32 s2, v254, 63
	v_readlane_b32 s4, v252, 16
	v_readlane_b32 s3, v255, 0
	s_lshl_b32 s2, s2, 26
	v_readlane_b32 s8, v252, 20
	s_add_u32 s4, s8, s2
	v_readlane_b32 s2, v254, 57
	v_readlane_b32 s5, v252, 17
	v_readlane_b32 s9, v252, 21
	v_lshlrev_b32_e32 v32, 1, v7
	v_readlane_b32 s3, v254, 58
	s_addc_u32 s5, s9, 0
	v_readlane_b32 s10, v252, 22
	v_lshl_add_u64 v[4:5], s[2:3], 0, v[32:33]
	s_lshl_b32 s2, s26, 8
	v_readlane_b32 s11, v252, 23
	v_lshl_add_u32 v11, v44, 2, s28
	v_mul_u32_u24_e32 v3, 0x84, v7
	v_or_b32_e32 v9, s2, v46
	s_add_i32 s2, s2, 0x32000
	v_add3_u32 v3, s28, v3, v6
	s_lshl_b32 s13, s27, 5
	v_or_b32_e32 v10, s2, v44
	v_add_u32_e32 v11, v11, v8
	s_mov_b32 s8, 0x48000
	s_mov_b32 s9, 0x54000
	s_mov_b32 s10, 0x58000
	s_mov_b32 s11, 0x5c000
	s_mov_b32 s90, 0x64000
	s_mov_b32 s91, 0x68000
	s_mov_b32 s31, 0x6c000
	s_mov_b32 s25, 0x74000
	s_mov_b32 s82, 0x78000
	s_movk_i32 s46, 0x4000
	v_readlane_b32 s6, v252, 18
	v_readlane_b32 s7, v252, 19

; #define LAS __attribute__((address_space(3)))
; __device__ __forceinline__ void transpose_item(const float* W, int K, int N, int NP, bf16* WT, LAS float* scr, int item, int lane, const LAS float* tab, long long* bias, int ldb, const float* kscale = nullptr) {
;     const int nblk = NP / 32, kb = item / nblk, nb = item - kb * nblk, k0 = 64 * kb, n0 = 32 * nb;
;     const int n = n0 + (lane & 31); const bool okn = n < N;
;     float wv_[32];
;     const float* wp = W + (size_t)(k0 + (lane >> 5)) * N + (okn ? n : 0);
; #pragma unroll
;     for (int i = 0; i < 32; ++i) wv_[i] = wp[(size_t)(2 * i) * N];
; __global__ void __launch_bounds__(NTHR, 2) fwd_kernel(Args a) {
;     ...
;           if (!lastl && rem != 0 && wg >= rem) { LAS float* scr = (LAS float*)(L + wave * 8448); LAS float* tab = (LAS float*)(L + 8 * 8448); const int worker = (wg - rem) * NWAVES + wave, nworkers = (G - rem) * NWAVES;
;               conv_load_tab(tab, modn, 3, tid); conv_A(csrc, cnext, l + 1, CV_A_SPLIT, CV_I1, worker, nworkers, scr, tab, biasn, lane); conv_B(csrc, cnext, l + 1, 0, CV_B_SPLIT, worker, nworkers, scr, lane); __syncthreads(); } }
.LBB0_1366:
	s_cmpk_gt_i32 s2, 0x1fff
	s_cbranch_scc1 .LBB0_1369
	v_readlane_b32 s4, v252, 16
	v_readlane_b32 s5, v252, 17
	v_readlane_b32 s3, v255, 1
	v_readlane_b32 s4, v255, 9
	s_lshl_b32 s3, s3, 26
	v_readlane_b32 s6, v252, 18
	v_readlane_b32 s8, v252, 20
	v_lshlrev_b32_e32 v32, 1, v11
	v_readlane_b32 s5, v255, 10
	v_readlane_b32 s7, v252, 19
	v_readlane_b32 s9, v252, 21
	v_readlane_b32 s11, v252, 23
	s_add_u32 s6, s8, s3
	v_lshl_add_u32 v5, v8, 2, s14
	v_mul_u32_u24_e32 v4, 0x84, v11
	v_lshl_add_u64 v[2:3], s[4:5], 0, v[32:33]
	s_mov_b64 s[4:5], 0x3b00000
	v_lshlrev_b32_e32 v6, 2, v9
	s_addc_u32 s7, s9, 0
	v_lshl_add_u64 v[2:3], v[2:3], 0, s[4:5]
	v_add3_u32 v4, s14, v4, v6
	s_lshl_b32 s3, s2, 5
	v_add_u32_e32 v5, v5, v10
	s_mov_b32 s11, 0x8000
	s_mov_b32 s12, 0x14000
	s_mov_b32 s13, 0x18000
	s_mov_b32 s14, 0x1c000
	s_mov_b32 s15, 0x24000
	s_mov_b32 s16, 0x28000
	s_mov_b32 s17, 0x2c000
	s_mov_b32 s19, 0x34000
	s_mov_b32 s22, 0x38000
	s_mov_b32 s23, 0x44000
	s_mov_b32 s25, 0x48000
	s_mov_b32 s26, 0x4c000
	s_mov_b32 s27, 0x54000
	s_mov_b32 s28, 0x58000
	s_mov_b32 s29, 0x5c000
	s_mov_b32 s30, 0x64000
	s_mov_b32 s31, 0x68000
	s_mov_b32 s33, 0x6c000
	s_mov_b32 s41, 0x74000
	s_movk_i32 s43, 0x4000
	v_readlane_b32 s10, v252, 22
.LBB0_1368:
	s_ashr_i32 s4, s2, 31
	s_lshr_b32 s4, s4, 26
	s_add_i32 s4, s2, s4
	s_and_b32 s8, s4, 0xffffffc0
	s_lshl_b32 s4, s4, 5
	s_and_b32 s4, s4, 0xfffff800
	s_sub_i32 s10, s3, s4
	v_add_u32_e32 v10, s10, v8
	v_or_b32_e32 v6, s8, v1
	v_cmp_gt_i32_e32 vcc, s56, v10
	v_ashrrev_i32_e32 v7, 31, v6
	v_lshlrev_b64 v[6:7], 13, v[6:7]
	v_cndmask_b32_e32 v10, 0, v10, vcc
	v_lshl_add_u64 v[6:7], s[6:7], 0, v[6:7]
	v_ashrrev_i32_e32 v11, 31, v10
	v_lshl_add_u64 v[36:37], v[10:11], 2, v[6:7]
	v_add_co_u32_e64 v6, s[4:5], s43, v36
	global_load_dword v35, v[36:37], off
	s_nop 0
	v_addc_co_u32_e64 v7, s[4:5], 0, v37, s[4:5]
	global_load_dword v38, v[6:7], off
	v_add_co_u32_e64 v6, s[4:5], s11, v36
	s_ashr_i32 s9, s8, 31
	s_nop 0
	v_addc_co_u32_e64 v7, s[4:5], 0, v37, s[4:5]
	global_load_dword v39, v[6:7], off
	v_add_co_u32_e64 v6, s[4:5], s18, v36
	s_add_i32 s2, s2, s24
	s_nop 0
	v_addc_co_u32_e64 v7, s[4:5], 0, v37, s[4:5]
	global_load_dword v40, v[6:7], off
	v_add_co_u32_e64 v6, s[4:5], s92, v36
	v_add_u32_e32 v8, s38, v8
	s_nop 0
	v_addc_co_u32_e64 v7, s[4:5], 0, v37, s[4:5]
	global_load_dword v41, v[6:7], off
	v_add_co_u32_e64 v6, s[4:5], s12, v36
	s_cmpk_lt_i32 s2, 0x2000
	s_nop 0
	v_addc_co_u32_e64 v7, s[4:5], 0, v37, s[4:5]
	global_load_dword v42, v[6:7], off
	v_add_co_u32_e64 v6, s[4:5], s13, v36
	s_nop 1
	v_addc_co_u32_e64 v7, s[4:5], 0, v37, s[4:5]
	global_load_dword v30, v[6:7], off
	v_add_co_u32_e64 v6, s[4:5], s14, v36
	s_nop 1
	v_addc_co_u32_e64 v7, s[4:5], 0, v37, s[4:5]
	global_load_dword v31, v[6:7], off
	v_add_co_u32_e64 v6, s[4:5], s78, v36
	s_nop 1
	v_addc_co_u32_e64 v7, s[4:5], 0, v37, s[4:5]
	global_load_dword v32, v[6:7], off
	v_add_co_u32_e64 v6, s[4:5], s15, v36
	s_nop 1
	v_addc_co_u32_e64 v7, s[4:5], 0, v37, s[4:5]
	global_load_dword v34, v[6:7], off
	v_add_co_u32_e64 v6, s[4:5], s16, v36
	s_nop 1
	v_addc_co_u32_e64 v7, s[4:5], 0, v37, s[4:5]
	global_load_dword v26, v[6:7], off
	v_add_co_u32_e64 v6, s[4:5], s17, v36
	s_nop 1
	v_addc_co_u32_e64 v7, s[4:5], 0, v37, s[4:5]
	global_load_dword v27, v[6:7], off
	v_add_co_u32_e64 v6, s[4:5], s49, v36
	s_nop 1
	v_addc_co_u32_e64 v7, s[4:5], 0, v37, s[4:5]
	global_load_dword v28, v[6:7], off
	v_add_co_u32_e64 v6, s[4:5], s19, v36
	s_nop 1
	v_addc_co_u32_e64 v7, s[4:5], 0, v37, s[4:5]
	global_load_dword v29, v[6:7], off
	v_add_co_u32_e64 v6, s[4:5], s22, v36
	s_nop 1
	v_addc_co_u32_e64 v7, s[4:5], 0, v37, s[4:5]
	global_load_dword v22, v[6:7], off
	v_add_co_u32_e64 v6, s[4:5], s39, v36
	s_nop 1
	v_addc_co_u32_e64 v7, s[4:5], 0, v37, s[4:5]
	global_load_dword v23, v[6:7], off
	v_add_co_u32_e64 v6, s[4:5], s79, v36
	s_nop 1
	v_addc_co_u32_e64 v7, s[4:5], 0, v37, s[4:5]
	global_load_dword v24, v[6:7], off
	v_add_co_u32_e64 v6, s[4:5], s23, v36
	s_nop 1
	v_addc_co_u32_e64 v7, s[4:5], 0, v37, s[4:5]
	global_load_dword v25, v[6:7], off
	v_add_co_u32_e64 v6, s[4:5], s25, v36
	s_nop 1
	v_addc_co_u32_e64 v7, s[4:5], 0, v37, s[4:5]
	global_load_dword v18, v[6:7], off
	v_add_co_u32_e64 v6, s[4:5], s26, v36
	s_nop 1
	v_addc_co_u32_e64 v7, s[4:5], 0, v37, s[4:5]
	global_load_dword v19, v[6:7], off
	v_add_co_u32_e64 v6, s[4:5], s0, v36
	s_nop 1
	v_addc_co_u32_e64 v7, s[4:5], 0, v37, s[4:5]
	global_load_dword v20, v[6:7], off
	v_add_co_u32_e64 v6, s[4:5], s27, v36
	s_nop 1
	v_addc_co_u32_e64 v7, s[4:5], 0, v37, s[4:5]
	global_load_dword v21, v[6:7], off
	v_add_co_u32_e64 v6, s[4:5], s28, v36
	s_nop 1
	v_addc_co_u32_e64 v7, s[4:5], 0, v37, s[4:5]
	global_load_dword v14, v[6:7], off
	v_add_co_u32_e64 v6, s[4:5], s29, v36
	s_nop 1
	v_addc_co_u32_e64 v7, s[4:5], 0, v37, s[4:5]
	global_load_dword v15, v[6:7], off
	v_add_co_u32_e64 v6, s[4:5], s40, v36
	s_nop 1
	v_addc_co_u32_e64 v7, s[4:5], 0, v37, s[4:5]
	global_load_dword v16, v[6:7], off
	v_add_co_u32_e64 v6, s[4:5], s30, v36
	s_nop 1
	v_addc_co_u32_e64 v7, s[4:5], 0, v37, s[4:5]
	global_load_dword v17, v[6:7], off
	v_add_co_u32_e64 v6, s[4:5], s31, v36
	s_nop 1
	v_addc_co_u32_e64 v7, s[4:5], 0, v37, s[4:5]
	global_load_dword v10, v[6:7], off
	v_add_co_u32_e64 v6, s[4:5], s33, v36
	s_nop 1
	v_addc_co_u32_e64 v7, s[4:5], 0, v37, s[4:5]
	global_load_dword v11, v[6:7], off
	v_add_co_u32_e64 v6, s[4:5], s96, v36
	s_nop 1
	v_addc_co_u32_e64 v7, s[4:5], 0, v37, s[4:5]
	global_load_dword v12, v[6:7], off
	v_add_co_u32_e64 v6, s[4:5], s41, v36
	s_nop 1
	v_addc_co_u32_e64 v7, s[4:5], 0, v37, s[4:5]
	global_load_dword v13, v[6:7], off
	v_add_co_u32_e64 v6, s[4:5], s42, v36
	s_nop 1
	v_addc_co_u32_e64 v7, s[4:5], 0, v37, s[4:5]
	v_add_co_u32_e64 v36, s[4:5], s83, v36
	global_load_dword v6, v[6:7], off
	s_nop 0
	v_addc_co_u32_e64 v37, s[4:5], 0, v37, s[4:5]
	global_load_dword v7, v[36:37], off
	s_waitcnt vmcnt(0)
; #define LAS __attribute__((address_space(3)))
; #define LDS_WAIT() asm volatile("s_waitcnt lgkmcnt(0)" ::: "memory")
; __device__ __forceinline__ unsigned pk2(float lo, float hi) { return pg8::pkbf(lo, hi); }
; __device__ __forceinline__ void transpose_item(const float* W, int K, int N, int NP, bf16* WT, LAS float* scr, int item, int lane, const LAS float* tab, long long* bias, int ldb, const float* kscale = nullptr) {
;     ...
;     for (int i = 0; i < 32; ++i) { if (!okn) wv_[i] = 0.f; if (kscale != nullptr) wv_[i] *= kscale[k0 + 2 * i + (lane >> 5)]; scr[(2 * i + (lane >> 5)) * 33 + (lane & 31)] = wv_[i]; }
;     if (tab != nullptr) {
;         const LAS float* tp = tab + k0 + (lane >> 5);
; #pragma unroll
;         for (int bp = 0; bp < 5; ++bp) { float s = 0.f;
; #pragma unroll
;             for (int i = 0; i < 32; ++i) s += tp[bp * 2048 + 2 * i] * wv_[i];
;             s += __shfl_xor(s, 32);
;             if (lane < 32) atomicAdd((unsigned long long*)(bias + (size_t)bp * ldb + n), (unsigned long long)(long long)(s * 4294967296.f)); }
;     }
;     LDS_WAIT(); asm volatile("" ::: "memory");
;     const int c = lane & 7;
; #pragma unroll
;     for (int j = 0; j < 4; ++j) { const int nn = (lane >> 3) + 8 * j; const LAS float* s = scr + (8 * c) * 33 + nn;
;         v4u o; o.x = pk2(s[0 * 33], s[1 * 33]); o.y = pk2(s[2 * 33], s[3 * 33]); o.z = pk2(s[4 * 33], s[5 * 33]); o.w = pk2(s[6 * 33], s[7 * 33]);
;         *(v4u*)(WT + (size_t)(n0 + nn) * K + k0 + 8 * c) = o; }
;     LDS_WAIT(); asm volatile("" ::: "memory");
	v_cndmask_b32_e32 v35, 0, v35, vcc
	v_cndmask_b32_e32 v30, 0, v30, vcc
	v_cndmask_b32_e32 v31, 0, v31, vcc
	v_cndmask_b32_e32 v26, 0, v26, vcc
	v_cndmask_b32_e32 v27, 0, v27, vcc
	v_cndmask_b32_e32 v22, 0, v22, vcc
	v_cndmask_b32_e32 v23, 0, v23, vcc
	v_cndmask_b32_e32 v18, 0, v18, vcc
	v_cndmask_b32_e32 v19, 0, v19, vcc
	v_cndmask_b32_e32 v14, 0, v14, vcc
	v_cndmask_b32_e32 v15, 0, v15, vcc
	v_cndmask_b32_e32 v10, 0, v10, vcc
	v_cndmask_b32_e32 v11, 0, v11, vcc
	v_add_u32_e32 v37, 0x400, v5
	ds_write2_b32 v37, v30, v31 offset0:140 offset1:206
	v_cndmask_b32_e32 v30, 0, v32, vcc
	v_add_u32_e32 v32, 0x800, v5
	ds_write2_b32 v32, v26, v27 offset0:148 offset1:214
	v_cndmask_b32_e32 v26, 0, v28, vcc
	v_add_u32_e32 v28, 0xc00, v5
	ds_write2_b32 v28, v22, v23 offset0:156 offset1:222
	v_cndmask_b32_e32 v22, 0, v24, vcc
	v_add_u32_e32 v24, 0x1000, v5
	v_cndmask_b32_e32 v36, 0, v38, vcc
	ds_write2_b32 v24, v18, v19 offset0:164 offset1:230
	v_cndmask_b32_e32 v18, 0, v20, vcc
	v_add_u32_e32 v20, 0x1400, v5
	ds_write2_b32 v5, v35, v36 offset1:66
	v_cndmask_b32_e32 v35, 0, v39, vcc
	v_cndmask_b32_e32 v36, 0, v40, vcc
	ds_write2_b32 v20, v14, v15 offset0:172 offset1:238
	v_cndmask_b32_e32 v14, 0, v16, vcc
	v_add_u32_e32 v16, 0x1800, v5
	ds_write2_b32 v5, v35, v36 offset0:132 offset1:198
	v_cndmask_b32_e32 v35, 0, v41, vcc
	v_cndmask_b32_e32 v36, 0, v42, vcc
	v_cndmask_b32_e32 v31, 0, v34, vcc
	v_cndmask_b32_e32 v27, 0, v29, vcc
	v_cndmask_b32_e32 v23, 0, v25, vcc
	v_cndmask_b32_e32 v19, 0, v21, vcc
	v_cndmask_b32_e32 v15, 0, v17, vcc
	ds_write2_b32 v16, v10, v11 offset0:180 offset1:246
	ds_write2_b32 v37, v35, v36 offset0:8 offset1:74
	ds_write2_b32 v32, v30, v31 offset0:16 offset1:82
	ds_write2_b32 v28, v26, v27 offset0:24 offset1:90
	ds_write2_b32 v24, v22, v23 offset0:32 offset1:98
	ds_write2_b32 v20, v18, v19 offset0:40 offset1:106
	ds_write2_b32 v16, v14, v15 offset0:48 offset1:114
	v_add_u32_e32 v30, s10, v9
	v_ashrrev_i32_e32 v31, 31, v30
	v_lshlrev_b64 v[34:35], 14, v[30:31]
	v_add_u32_e32 v9, s38, v9
	s_waitcnt vmcnt(3)
	v_cndmask_b32_e32 v10, 0, v12, vcc
	v_add_u32_e32 v12, 0x1c00, v5
	s_waitcnt vmcnt(2)
	v_cndmask_b32_e32 v11, 0, v13, vcc
	ds_write2_b32 v12, v10, v11 offset0:56 offset1:122
	s_waitcnt vmcnt(1)
	v_cndmask_b32_e32 v6, 0, v6, vcc
	s_waitcnt vmcnt(0)
	v_cndmask_b32_e32 v7, 0, v7, vcc
	ds_write2_b32 v12, v6, v7 offset0:188 offset1:254
	s_waitcnt lgkmcnt(0)
	ds_read2_b32 v[14:15], v4 offset0:33 offset1:41
	ds_read2_b32 v[16:17], v4 offset1:8
	ds_read2_b32 v[18:19], v4 offset0:66 offset1:74
	ds_read2_b32 v[20:21], v4 offset0:99 offset1:107
	ds_read2_b32 v[22:23], v4 offset0:132 offset1:140
	ds_read2_b32 v[24:25], v4 offset0:165 offset1:173
	ds_read2_b32 v[26:27], v4 offset0:198 offset1:206
	ds_read2_b32 v[28:29], v4 offset0:231 offset1:239
	v_lshl_add_u64 v[6:7], s[8:9], 1, v[2:3]
	s_waitcnt lgkmcnt(6)
	v_cvt_pk_bf16_f32 v10, v16, v14
	s_waitcnt lgkmcnt(4)
	v_cvt_pk_bf16_f32 v11, v18, v20
	s_waitcnt lgkmcnt(2)
	v_cvt_pk_bf16_f32 v12, v22, v24
	s_waitcnt lgkmcnt(0)
	v_cvt_pk_bf16_f32 v13, v26, v28
	v_lshl_add_u64 v[34:35], v[6:7], 0, v[34:35]
	v_add_u32_e32 v14, 8, v30
	global_store_dwordx4 v[34:35], v[10:13], off
	v_add_u32_e32 v34, 16, v30
	v_ashrrev_i32_e32 v35, 31, v34
	v_cvt_pk_bf16_f32 v10, v17, v15
	v_ashrrev_i32_e32 v15, 31, v14
	v_lshlrev_b64 v[14:15], 14, v[14:15]
	v_cvt_pk_bf16_f32 v11, v19, v21
	v_cvt_pk_bf16_f32 v12, v23, v25
	v_cvt_pk_bf16_f32 v13, v27, v29
	v_lshl_add_u64 v[14:15], v[6:7], 0, v[14:15]
	global_store_dwordx4 v[14:15], v[10:13], off
	ds_read2_b32 v[14:15], v4 offset0:49 offset1:57
	ds_read2_b32 v[16:17], v4 offset0:16 offset1:24
	ds_read2_b32 v[18:19], v4 offset0:82 offset1:90
	ds_read2_b32 v[20:21], v4 offset0:115 offset1:123
	ds_read2_b32 v[22:23], v4 offset0:148 offset1:156
	ds_read2_b32 v[24:25], v4 offset0:181 offset1:189
	ds_read2_b32 v[26:27], v4 offset0:214 offset1:222
	ds_read2_b32 v[28:29], v4 offset0:247 offset1:255
	v_lshlrev_b64 v[34:35], 14, v[34:35]
	s_waitcnt lgkmcnt(6)
	v_cvt_pk_bf16_f32 v10, v16, v14
	s_waitcnt lgkmcnt(4)
	v_cvt_pk_bf16_f32 v11, v18, v20
	s_waitcnt lgkmcnt(2)
	v_cvt_pk_bf16_f32 v12, v22, v24
	s_waitcnt lgkmcnt(0)
	v_cvt_pk_bf16_f32 v13, v26, v28
	v_lshl_add_u64 v[34:35], v[6:7], 0, v[34:35]
	v_add_u32_e32 v14, 24, v30
	global_store_dwordx4 v[34:35], v[10:13], off
	s_nop 1
	v_cvt_pk_bf16_f32 v10, v17, v15
	v_ashrrev_i32_e32 v15, 31, v14
	v_lshlrev_b64 v[14:15], 14, v[14:15]
	v_cvt_pk_bf16_f32 v11, v19, v21
	v_cvt_pk_bf16_f32 v12, v23, v25
	v_cvt_pk_bf16_f32 v13, v27, v29
	v_lshl_add_u64 v[6:7], v[6:7], 0, v[14:15]
	global_store_dwordx4 v[6:7], v[10:13], off
	s_waitcnt lgkmcnt(0)
	s_cbranch_scc1 .LBB0_1368
